# ph10: blocks < 256 run their short 256-key unit before the long one (co-resident long units out of step)
# baseline (speedup 1.0000x reference)
.LBB0_1060:
	s_cmp_gt_i32 s22, 10
	s_cselect_b64 s[4:5], -1, 0
	s_cmp_lt_i32 s23, 11
	s_cselect_b64 s[6:7], -1, 0
	s_or_b64 s[4:5], s[4:5], s[6:7]
	s_and_b64 vcc, exec, s[4:5]
	s_cbranch_vccnz .LBB0_1130
	s_cmpk_gt_i32 s2, 0x2ff
	v_and_b32_e32 v147, 0x3ff, v0
	s_cbranch_scc1 .LBB0_1077
	s_waitcnt vmcnt(0)
	v_lshrrev_b32_e32 v2, 1, v147
	v_and_b32_e32 v151, 0x1e0, v2
	v_lshrrev_b32_e32 v2, 4, v147
	v_xor_b32_e32 v6, v2, v147
	v_lshlrev_b32_e32 v7, 3, v6
	v_and_b32_e32 v6, 0x78, v7
	v_and_b32_e32 v8, 56, v7
	v_lshlrev_b32_e32 v7, 4, v147
	s_load_dwordx8 s[4:11], s[0:1], 0x140
	v_lshrrev_b32_e32 v5, 5, v147
	v_and_b32_e32 v177, 0x3c00, v7
	v_and_b32_e32 v7, 15, v147
	v_bfe_u32 v175, v147, 5, 1
	v_bitop3_b32 v9, v5, v7, 1 bitop3:0x6c
	v_lshrrev_b32_e32 v176, 3, v147
	v_lshlrev_b32_e32 v180, 4, v9
	v_bitop3_b32 v9, v175, v7, 2 bitop3:0x36
	v_lshlrev_b32_e32 v4, 10, v2
	v_mov_b32_e32 v3, 0
	v_lshlrev_b32_e32 v2, 7, v176
	v_bfe_u32 v178, v147, 1, 3
	v_lshlrev_b32_e32 v181, 4, v9
	v_bitop3_b32 v9, v175, v7, 4 bitop3:0x36
	v_lshlrev_b32_e32 v182, 4, v9
	v_bitop3_b32 v9, v175, v7, 6 bitop3:0x36
	v_bitop3_b32 v5, v5, v178, 1 bitop3:0x6c
	s_load_dwordx2 s[14:15], s[0:1], 0x98
	s_load_dwordx2 s[16:17], s[0:1], 0x128
	s_waitcnt lgkmcnt(0)
	v_lshl_add_u64 v[14:15], s[4:5], 0, v[2:3]
	v_lshlrev_b32_e32 v2, 1, v8
	v_lshlrev_b32_e32 v183, 4, v9
	v_bitop3_b32 v9, v175, v7, 8 bitop3:0x36
	v_lshlrev_b32_e32 v188, 4, v5
	v_bitop3_b32 v5, v175, v178, 2 bitop3:0x36
	v_lshl_add_u64 v[152:153], v[14:15], 0, v[2:3]
	v_mbcnt_lo_u32_b32 v2, -1, 0
	v_lshlrev_b32_e32 v184, 4, v9
	v_bitop3_b32 v9, v175, v7, 10 bitop3:0x36
	v_lshlrev_b32_e32 v189, 4, v5
	v_bitop3_b32 v5, v175, v178, 4 bitop3:0x36
	v_mbcnt_hi_u32_b32 v201, -1, v2
	v_and_b32_e32 v149, 31, v147
	v_lshlrev_b32_e32 v10, 3, v175
	v_lshlrev_b32_e32 v185, 4, v9
	v_bitop3_b32 v9, v175, v7, 12 bitop3:0x36
	v_bitop3_b32 v7, v175, v7, 14 bitop3:0x36
	v_lshlrev_b32_e32 v190, 4, v5
	v_bitop3_b32 v5, v175, v178, 6 bitop3:0x36
	v_lshlrev_b32_e32 v12, 2, v175
	s_add_u32 s12, s0, 0x468
	v_and_b32_e32 v2, 64, v201
	v_or_b32_e32 v174, 0x1000, v151
	v_lshlrev_b32_e32 v179, 7, v149
	v_lshlrev_b32_e32 v186, 4, v9
	v_lshlrev_b32_e32 v187, 4, v7
	v_lshlrev_b32_e32 v191, 4, v5
	s_addc_u32 s13, s1, 0
	s_mov_b32 s5, 0
	s_movk_i32 s3, 0xc00
	v_mov_b64_e32 v[154:155], s[6:7]
	v_lshlrev_b32_e32 v156, 1, v10
	v_mov_b32_e32 v157, v3
	v_lshlrev_b32_e32 v158, 1, v4
	v_mov_b32_e32 v159, v3
	v_lshlrev_b32_e32 v160, 1, v8
	v_mov_b32_e32 v161, v3
	v_lshlrev_b32_e32 v162, 1, v6
	v_mov_b32_e32 v163, v3
	s_mov_b64 s[6:7], 0x8000
	v_add_u32_e32 v192, 0x1000, v177
	s_mov_b64 s[18:19], 0x10000
	v_add_u32_e32 v193, 0x2000, v177
	s_mov_b64 s[24:25], 0x18000
	v_add_u32_e32 v194, 0x3000, v177
	v_or_b32_e32 v195, 0x4000, v177
	s_mov_b64 s[26:27], 0x1000
	v_add_u32_e32 v196, 0x5000, v177
	v_add_u32_e32 v197, 0x6000, v177
	v_add_u32_e32 v198, 0x7000, v177
	v_or_b32_e32 v199, 0x8000, v177
	v_add_u32_e32 v200, 0x9000, v177
	s_mov_b64 s[28:29], 0x80
	v_lshlrev_b32_e32 v164, 1, v12
	v_xor_b32_e32 v202, 32, v201
	v_add_u32_e32 v203, 64, v2
	s_mov_b32 s42, s2
	s_load_dword s96, s[12:13], 0x0
	s_waitcnt lgkmcnt(0)
	s_cmpk_lg_u32 s96, 0x200
	s_cbranch_scc1 .Lph10_order_done
	s_cmpk_gt_u32 s2, 0xff
	s_cbranch_scc1 .Lph10_order_done
	s_add_i32 s42, s2, 0x200
	s_movk_i32 s96, 0xfe00

.LBB0_1063:
	v_lshlrev_b64 v[6:7], 11, v[166:167]
	v_lshl_add_u64 v[4:5], s[14:15], 0, v[6:7]
	s_lshl_b32 s4, s44, 1
	v_lshl_add_u64 v[4:5], v[4:5], 0, s[4:5]
	v_mov_b32_e32 v165, v3
	v_lshl_add_u64 v[4:5], v[4:5], 0, v[164:165]
	global_load_dwordx2 v[8:9], v[4:5], off
	global_load_dwordx2 v[10:11], v[4:5], off offset:16
	global_load_dwordx2 v[12:13], v[4:5], off offset:32
	global_load_dwordx2 v[14:15], v[4:5], off offset:48
	global_load_dwordx2 v[16:17], v[4:5], off offset:64
	global_load_dwordx2 v[82:83], v[4:5], off offset:80
	global_load_dwordx2 v[84:85], v[4:5], off offset:96
	global_load_dwordx2 v[86:87], v[4:5], off offset:112
	ds_bpermute_b32 v2, v205, v204
	global_load_dwordx2 v[88:89], v[4:5], off offset:128
	global_load_dwordx2 v[90:91], v[4:5], off offset:144
	global_load_dwordx2 v[92:93], v[4:5], off offset:160
	global_load_dwordx2 v[94:95], v[4:5], off offset:176
	v_lshl_add_u64 v[6:7], s[16:17], 0, v[6:7]
	v_lshl_add_u64 v[6:7], v[6:7], 0, s[4:5]
	v_lshl_add_u64 v[6:7], v[6:7], 0, v[164:165]
	s_waitcnt lgkmcnt(0)
	v_add_f32_e32 v2, v204, v2
	v_div_scale_f32 v96, s[30:31], v2, v2, 1.0
	v_rcp_f32_e32 v97, v96
	v_div_scale_f32 v98, vcc, 1.0, v2, 1.0
	v_fma_f32 v99, -v96, v97, 1.0
	v_fmac_f32_e32 v97, v99, v97
	v_mul_f32_e32 v99, v98, v97
	v_fma_f32 v100, -v96, v99, v98
	v_fmac_f32_e32 v99, v100, v97
	v_fma_f32 v96, -v96, v99, v98
	v_div_fmas_f32 v96, v96, v97, v99
	v_div_fixup_f32 v2, v96, v2, 1.0
	v_pk_mul_f32 v[66:67], v[66:67], v[2:3] op_sel_hi:[1,0]
	v_pk_mul_f32 v[68:69], v[68:69], v[2:3] op_sel_hi:[1,0]
	v_pk_mul_f32 v[70:71], v[70:71], v[2:3] op_sel_hi:[1,0]
	v_pk_mul_f32 v[72:73], v[72:73], v[2:3] op_sel_hi:[1,0]
	v_pk_mul_f32 v[74:75], v[74:75], v[2:3] op_sel_hi:[1,0]
	v_pk_mul_f32 v[76:77], v[76:77], v[2:3] op_sel_hi:[1,0]
	v_pk_mul_f32 v[78:79], v[78:79], v[2:3] op_sel_hi:[1,0]
	v_pk_mul_f32 v[80:81], v[80:81], v[2:3] op_sel_hi:[1,0]
	v_pk_mul_f32 v[50:51], v[50:51], v[2:3] op_sel_hi:[1,0]
	s_waitcnt vmcnt(11)
	v_lshlrev_b32_e32 v96, 16, v8
	v_and_b32_e32 v97, 0xffff0000, v8
	v_lshlrev_b32_e32 v8, 16, v9
	v_and_b32_e32 v9, 0xffff0000, v9
	s_waitcnt vmcnt(10)
	v_lshlrev_b32_e32 v98, 16, v10
	v_and_b32_e32 v99, 0xffff0000, v10
	v_lshlrev_b32_e32 v10, 16, v11
	v_and_b32_e32 v11, 0xffff0000, v11
	s_waitcnt vmcnt(9)
	v_lshlrev_b32_e32 v100, 16, v12
	v_and_b32_e32 v101, 0xffff0000, v12
	v_lshlrev_b32_e32 v12, 16, v13
	v_and_b32_e32 v13, 0xffff0000, v13
	s_waitcnt vmcnt(8)
	v_lshlrev_b32_e32 v102, 16, v14
	v_and_b32_e32 v103, 0xffff0000, v14
	v_lshlrev_b32_e32 v14, 16, v15
	v_and_b32_e32 v15, 0xffff0000, v15
	v_pk_mul_f32 v[66:67], v[66:67], v[96:97]
	v_pk_mul_f32 v[8:9], v[68:69], v[8:9]
	v_pk_mul_f32 v[68:69], v[70:71], v[98:99]
	v_pk_mul_f32 v[10:11], v[72:73], v[10:11]
	v_pk_mul_f32 v[70:71], v[74:75], v[100:101]
	v_pk_mul_f32 v[12:13], v[76:77], v[12:13]
	v_pk_mul_f32 v[72:73], v[78:79], v[102:103]
	v_pk_mul_f32 v[14:15], v[80:81], v[14:15]
	v_cvt_pk_bf16_f32 v66, v66, v67
	v_cvt_pk_bf16_f32 v67, v8, v9
	v_cvt_pk_bf16_f32 v8, v68, v69
	v_cvt_pk_bf16_f32 v9, v10, v11
	s_waitcnt vmcnt(7)
	v_lshlrev_b32_e32 v104, 16, v16
	v_and_b32_e32 v105, 0xffff0000, v16
	v_lshlrev_b32_e32 v16, 16, v17
	v_and_b32_e32 v17, 0xffff0000, v17
	v_cvt_pk_bf16_f32 v10, v70, v71
	v_cvt_pk_bf16_f32 v11, v12, v13
	v_cvt_pk_bf16_f32 v12, v72, v73
	v_cvt_pk_bf16_f32 v13, v14, v15
	global_store_dwordx2 v[6:7], v[66:67], off
	global_store_dwordx2 v[6:7], v[8:9], off offset:16
	global_store_dwordx2 v[6:7], v[10:11], off offset:32
	global_store_dwordx2 v[6:7], v[12:13], off offset:48
	v_pk_mul_f32 v[8:9], v[52:53], v[2:3] op_sel_hi:[1,0]
	v_pk_mul_f32 v[50:51], v[50:51], v[104:105]
	v_pk_mul_f32 v[8:9], v[8:9], v[16:17]
	global_load_dwordx2 v[10:11], v[4:5], off offset:192
	v_cvt_pk_bf16_f32 v14, v50, v51
	v_cvt_pk_bf16_f32 v15, v8, v9
	s_waitcnt vmcnt(11)
	v_lshlrev_b32_e32 v8, 16, v82
	v_and_b32_e32 v9, 0xffff0000, v82
	v_pk_mul_f32 v[12:13], v[54:55], v[2:3] op_sel_hi:[1,0]
	global_store_dwordx2 v[6:7], v[14:15], off offset:64
	v_pk_mul_f32 v[8:9], v[12:13], v[8:9]
	v_lshlrev_b32_e32 v12, 16, v83
	v_and_b32_e32 v13, 0xffff0000, v83
	v_pk_mul_f32 v[14:15], v[56:57], v[2:3] op_sel_hi:[1,0]
	v_cvt_pk_bf16_f32 v8, v8, v9
	v_pk_mul_f32 v[12:13], v[14:15], v[12:13]
	v_pk_mul_f32 v[14:15], v[58:59], v[2:3] op_sel_hi:[1,0]
	v_cvt_pk_bf16_f32 v9, v12, v13
	global_store_dwordx2 v[6:7], v[8:9], off offset:80
	global_load_dwordx2 v[8:9], v[4:5], off offset:208
	s_waitcnt vmcnt(13)
	v_lshlrev_b32_e32 v12, 16, v84
	v_and_b32_e32 v13, 0xffff0000, v84
	v_pk_mul_f32 v[12:13], v[14:15], v[12:13]
	v_lshlrev_b32_e32 v14, 16, v85
	v_and_b32_e32 v15, 0xffff0000, v85
	v_pk_mul_f32 v[16:17], v[60:61], v[2:3] op_sel_hi:[1,0]
	v_cvt_pk_bf16_f32 v12, v12, v13
	v_pk_mul_f32 v[14:15], v[16:17], v[14:15]
	v_pk_mul_f32 v[16:17], v[62:63], v[2:3] op_sel_hi:[1,0]
	v_cvt_pk_bf16_f32 v13, v14, v15
	global_load_dwordx2 v[14:15], v[4:5], off offset:224
	v_pk_mul_f32 v[50:51], v[64:65], v[2:3] op_sel_hi:[1,0]
	global_load_dwordx2 v[4:5], v[4:5], off offset:240
	s_nop 0
	global_store_dwordx2 v[6:7], v[12:13], off offset:96
	s_waitcnt vmcnt(15)
	v_lshlrev_b32_e32 v12, 16, v86
	v_and_b32_e32 v13, 0xffff0000, v86
	v_pk_mul_f32 v[12:13], v[16:17], v[12:13]
	v_lshlrev_b32_e32 v16, 16, v87
	v_and_b32_e32 v17, 0xffff0000, v87
	v_pk_mul_f32 v[16:17], v[50:51], v[16:17]
	v_cvt_pk_bf16_f32 v12, v12, v13
	v_cvt_pk_bf16_f32 v13, v16, v17
	global_store_dwordx2 v[6:7], v[12:13], off offset:112
	s_waitcnt vmcnt(15)
	v_lshlrev_b32_e32 v12, 16, v88
	v_and_b32_e32 v13, 0xffff0000, v88
	v_pk_mul_f32 v[16:17], v[34:35], v[2:3] op_sel_hi:[1,0]
	v_pk_mul_f32 v[34:35], v[36:37], v[2:3] op_sel_hi:[1,0]
	v_pk_mul_f32 v[12:13], v[16:17], v[12:13]
	v_lshlrev_b32_e32 v16, 16, v89
	v_and_b32_e32 v17, 0xffff0000, v89
	v_pk_mul_f32 v[16:17], v[34:35], v[16:17]
	v_cvt_pk_bf16_f32 v12, v12, v13
	v_cvt_pk_bf16_f32 v13, v16, v17
	global_store_dwordx2 v[6:7], v[12:13], off offset:128
	s_waitcnt vmcnt(15)
	v_lshlrev_b32_e32 v12, 16, v90
	v_and_b32_e32 v13, 0xffff0000, v90
	v_pk_mul_f32 v[16:17], v[38:39], v[2:3] op_sel_hi:[1,0]
	v_pk_mul_f32 v[34:35], v[40:41], v[2:3] op_sel_hi:[1,0]
	v_pk_mul_f32 v[12:13], v[16:17], v[12:13]
	v_lshlrev_b32_e32 v16, 16, v91
	v_and_b32_e32 v17, 0xffff0000, v91
	v_pk_mul_f32 v[16:17], v[34:35], v[16:17]
	v_cvt_pk_bf16_f32 v12, v12, v13
	v_cvt_pk_bf16_f32 v13, v16, v17
	global_store_dwordx2 v[6:7], v[12:13], off offset:144
	s_waitcnt vmcnt(15)
	v_lshlrev_b32_e32 v12, 16, v92
	v_and_b32_e32 v13, 0xffff0000, v92
	v_pk_mul_f32 v[16:17], v[42:43], v[2:3] op_sel_hi:[1,0]
	v_pk_mul_f32 v[34:35], v[44:45], v[2:3] op_sel_hi:[1,0]
	v_pk_mul_f32 v[12:13], v[16:17], v[12:13]
	v_lshlrev_b32_e32 v16, 16, v93
	v_and_b32_e32 v17, 0xffff0000, v93
	v_pk_mul_f32 v[16:17], v[34:35], v[16:17]
	v_cvt_pk_bf16_f32 v12, v12, v13
	v_cvt_pk_bf16_f32 v13, v16, v17
	global_store_dwordx2 v[6:7], v[12:13], off offset:160
	s_waitcnt vmcnt(15)
	v_lshlrev_b32_e32 v12, 16, v94
	v_and_b32_e32 v13, 0xffff0000, v94
	v_pk_mul_f32 v[16:17], v[46:47], v[2:3] op_sel_hi:[1,0]
	v_pk_mul_f32 v[34:35], v[48:49], v[2:3] op_sel_hi:[1,0]
	v_pk_mul_f32 v[12:13], v[16:17], v[12:13]
	v_lshlrev_b32_e32 v16, 16, v95
	v_and_b32_e32 v17, 0xffff0000, v95
	v_pk_mul_f32 v[16:17], v[34:35], v[16:17]
	v_cvt_pk_bf16_f32 v12, v12, v13
	v_cvt_pk_bf16_f32 v13, v16, v17
	global_store_dwordx2 v[6:7], v[12:13], off offset:176
	s_waitcnt vmcnt(11)
	v_lshlrev_b32_e32 v12, 16, v10
	v_and_b32_e32 v13, 0xffff0000, v10
	v_pk_mul_f32 v[16:17], v[18:19], v[2:3] op_sel_hi:[1,0]
	s_nop 0
	v_pk_mul_f32 v[12:13], v[16:17], v[12:13]
	v_pk_mul_f32 v[16:17], v[20:21], v[2:3] op_sel_hi:[1,0]
	v_cvt_pk_bf16_f32 v10, v12, v13
	v_lshlrev_b32_e32 v12, 16, v11
	v_and_b32_e32 v13, 0xffff0000, v11
	v_pk_mul_f32 v[12:13], v[16:17], v[12:13]
	s_nop 0
	v_cvt_pk_bf16_f32 v11, v12, v13
	global_store_dwordx2 v[6:7], v[10:11], off offset:192
	s_waitcnt vmcnt(9)
	v_lshlrev_b32_e32 v10, 16, v8
	v_and_b32_e32 v11, 0xffff0000, v8
	v_pk_mul_f32 v[12:13], v[22:23], v[2:3] op_sel_hi:[1,0]
	s_nop 0
	v_pk_mul_f32 v[10:11], v[12:13], v[10:11]
	v_pk_mul_f32 v[12:13], v[24:25], v[2:3] op_sel_hi:[1,0]
	v_cvt_pk_bf16_f32 v8, v10, v11
	v_lshlrev_b32_e32 v10, 16, v9
	v_and_b32_e32 v11, 0xffff0000, v9
	v_pk_mul_f32 v[10:11], v[12:13], v[10:11]
	v_pk_mul_f32 v[12:13], v[28:29], v[2:3] op_sel_hi:[1,0]
	v_cvt_pk_bf16_f32 v9, v10, v11
	global_store_dwordx2 v[6:7], v[8:9], off offset:208
	s_waitcnt vmcnt(9)
	v_lshlrev_b32_e32 v8, 16, v14
	v_and_b32_e32 v9, 0xffff0000, v14
	v_pk_mul_f32 v[10:11], v[26:27], v[2:3] op_sel_hi:[1,0]
	s_nop 0
	v_pk_mul_f32 v[8:9], v[10:11], v[8:9]
	v_lshlrev_b32_e32 v10, 16, v15
	v_and_b32_e32 v11, 0xffff0000, v15
	v_pk_mul_f32 v[10:11], v[12:13], v[10:11]
	v_cvt_pk_bf16_f32 v8, v8, v9
	v_cvt_pk_bf16_f32 v9, v10, v11
	global_store_dwordx2 v[6:7], v[8:9], off offset:224
	s_waitcnt vmcnt(9)
	v_lshlrev_b32_e32 v8, 16, v4
	v_and_b32_e32 v9, 0xffff0000, v4
	v_pk_mul_f32 v[10:11], v[30:31], v[2:3] op_sel_hi:[1,0]
	s_nop 0
	v_pk_mul_f32 v[8:9], v[10:11], v[8:9]
	v_pk_mul_f32 v[10:11], v[32:33], v[2:3] op_sel_hi:[1,0]
	v_cvt_pk_bf16_f32 v4, v8, v9
	v_lshlrev_b32_e32 v8, 16, v5
	v_and_b32_e32 v9, 0xffff0000, v5
	v_pk_mul_f32 v[8:9], v[10:11], v[8:9]
	s_nop 0
	v_cvt_pk_bf16_f32 v5, v8, v9
	global_store_dwordx2 v[6:7], v[4:5], off offset:240
	s_mov_b32 s4, s96
	s_waitcnt lgkmcnt(0)
	s_add_i32 s42, s4, s42
	s_cmpk_lt_u32 s42, 0x300
	s_cbranch_scc0 .LBB0_1077
